# P7 out-proj GEMM residual epilogue: hand-written fast path with 5-deep x prefetch and counted vmcnt
# speedup vs baseline: 1.0055x; 1.0055x over previous
; template <class Epi>
; DEVI void gemm_phase(const Params& p, const u16* __restrict__ A, const u16* __restrict__ Bt, const int M, const int N, const int K, const int Msplit, const Epi& epi) {
;     ...
;           const int colb = bcol + bj * HALF + wc2 * 32;
;           typename Epi::Pre pre;
;           if constexpr (Epi::NRM || Epi::SQ) epi.preload(pre, brow, colb, wr2, fr2, fq2, nrm, slcur);
;   DEVI void preload(Pre& q, int brow, int colb, int wr, int fr, int fq, bool, int slice) const {
;     if (slice >= 0) return;
;     const int r = brow < TL ? (brow >> 12) : 8;
;     const float* gate = modl + (size_t)(r * 9 + gi) * D;
; #pragma unroll
;     for (int n = 0; n < 2; ++n) {
;       const int col = colb + n * 16 + 4 * fq;
;       q.gv[n] = *(const f32x4*)(gate + col);
;       if (xg) q.G[n] = *(const f32x4*)(gvl + (size_t)r * D + col);
.LBB0_1728:
	s_cmpk_lt_i32 s1, 0x80
	s_cbranch_scc1 .Lmy_p7_epi
	v_mbcnt_lo_u32_b32 v145, -1, 0
	v_mbcnt_hi_u32_b32 v145, -1, v145
	s_cmpk_gt_i32 s1, 0x7f
	v_or_b32_e32 v150, s33, v145
	v_lshrrev_b32_e32 v112, 1, v150
	s_cselect_b64 s[12:13], -1, 0
	s_cmpk_lt_i32 s1, 0x80
	v_and_b32_e32 v112, 0x60, v112
	s_cselect_b64 s[36:37], -1, 0
	v_or_b32_e32 v144, s24, v112
	v_lshrrev_b32_e32 v112, 2, v145
	s_min_i32 s1, s10, 0x8000
	v_and_b32_e32 v212, 12, v112
	s_ashr_i32 s1, s1, 12
	s_mul_i32 s26, s1, 9
	s_mov_b64 s[24:25], -1
	s_and_b64 vcc, exec, s[36:37]
	v_or_b32_e32 v146, v144, v212
	s_cbranch_vccz .LBB0_1730
	s_ashr_i32 s27, s26, 31
	s_lshl_b64 s[16:17], s[26:27], 12
	s_add_u32 s16, s94, s16
	s_addc_u32 s17, s95, s17
	v_ashrrev_i32_e32 v147, 31, v146
	v_lshl_add_u64 v[112:113], v[146:147], 2, s[16:17]
	s_mov_b64 s[16:17], 0x5000
	v_lshl_add_u64 v[116:117], v[112:113], 0, s[16:17]
	v_add_co_u32_e32 v112, vcc, 0x5000, v112
	v_or_b32_e32 v148, 16, v146
	s_nop 0
	v_addc_co_u32_e32 v113, vcc, 0, v113, vcc
	global_load_dwordx4 v[112:115], v[112:113], off
	s_nop 0
	global_load_dwordx4 v[116:119], v[116:117], off offset:64
	v_ashrrev_i32_e32 v149, 31, v148
	s_mov_b64 s[24:25], 0

;   DEVI void operator()(int row, int colb, int fq, const f32x4& a0, const f32x4& a1, float& sqacc, const int slice, const Pre& q) const {
;     ...
;     const float* src = row < TL ? xin_lat + (size_t)row * D : xin_ctx + (size_t)(row - TL) * D;
;     const f32x4 xi0 = *(const f32x4*)(src + colb + 4 * fq), xi1 = *(const f32x4*)(src + colb + 16 + 4 * fq);
; #pragma unroll
;     for (int n = 0; n < 2; ++n) {
;       const int col = colb + n * 16 + 4 * fq;
;       const f32x4& a = n ? a1 : a0; const f32x4& xi = n ? xi1 : xi0;
;       f32x4 o;
; #pragma unroll
;       for (int j = 0; j < 4; ++j) o[j] = xi[j] + coef * q.gv[n][j] * a[j];
;       *(f32x4*)(xout + (size_t)row * D + col) = o;
.Lmy_p7_epi:
	v_mbcnt_lo_u32_b32 v149, -1, 0
	v_mbcnt_hi_u32_b32 v149, -1, v149
	s_lshr_b32 s44, s33, 6
	s_lshr_b32 s45, s44, 2
	s_and_b32 s44, s44, 3
	s_lshl_b32 s45, s45, 18
	s_lshl_b32 s44, s44, 7
	v_and_b32_e32 v150, 15, v149
	v_lshrrev_b32_e32 v149, 4, v149
	v_lshl_add_u32 v148, v149, 4, s44
	v_lshl_add_u32 v150, v150, 12, s45
	v_add_u32_e32 v144, v150, v148
	v_add_u32_e32 v145, 0x10000, v144
	v_add_u32_e32 v146, 0x20000, v144
	v_add_u32_e32 v147, 0x30000, v144
	s_lshl_b32 s46, s10, 12
	s_lshl_b32 s47, s24, 2
	s_add_u32 s46, s46, s47
	s_add_u32 s36, s70, s46
	s_addc_u32 s37, s71, 0
	s_add_u32 s38, s36, 0x80000
	s_addc_u32 s39, s37, 0
	s_lshr_b32 s46, s10, 12
	s_mul_i32 s46, s46, 9
	s_add_i32 s46, s46, 5
	s_lshl_b32 s46, s46, 12
	s_add_u32 s46, s46, s47
	s_add_u32 s40, s94, s46
	s_addc_u32 s41, s95, 0
	global_load_dwordx4 v[112:115], v148, s[40:41]
	global_load_dwordx4 v[116:119], v148, s[40:41] offset:64
	global_load_dwordx4 v[200:203], v148, s[40:41] offset:512
	global_load_dwordx4 v[204:207], v148, s[40:41] offset:576
	global_load_dwordx4 v[152:155], v144, s[36:37]
	global_load_dwordx4 v[156:159], v144, s[36:37] offset:64
	global_load_dwordx4 v[160:163], v145, s[36:37]
	global_load_dwordx4 v[164:167], v145, s[36:37] offset:64
	global_load_dwordx4 v[168:171], v146, s[36:37]
	global_load_dwordx4 v[172:175], v146, s[36:37] offset:64
	global_load_dwordx4 v[176:179], v147, s[36:37]
	global_load_dwordx4 v[180:183], v147, s[36:37] offset:64
	global_load_dwordx4 v[184:187], v144, s[36:37] offset:512
	global_load_dwordx4 v[188:191], v144, s[36:37] offset:576
	s_waitcnt vmcnt(8)
	v_pk_fma_f32 v[152:153], v[140:141], v[112:113], v[152:153]
	v_pk_fma_f32 v[154:155], v[142:143], v[114:115], v[154:155]
	v_pk_fma_f32 v[156:157], v[136:137], v[116:117], v[156:157]
	v_pk_fma_f32 v[158:159], v[138:139], v[118:119], v[158:159]
	global_store_dwordx4 v144, v[152:155], s[36:37]
	global_store_dwordx4 v144, v[156:159], s[36:37] offset:64
	global_load_dwordx4 v[192:195], v145, s[36:37] offset:512
	global_load_dwordx4 v[196:199], v145, s[36:37] offset:576
	s_waitcnt vmcnt(10)
	v_pk_fma_f32 v[160:161], v[132:133], v[112:113], v[160:161]
	v_pk_fma_f32 v[162:163], v[134:135], v[114:115], v[162:163]
	v_pk_fma_f32 v[164:165], v[128:129], v[116:117], v[164:165]
	v_pk_fma_f32 v[166:167], v[130:131], v[118:119], v[166:167]
	global_store_dwordx4 v145, v[160:163], s[36:37]
	global_store_dwordx4 v145, v[164:167], s[36:37] offset:64
	global_load_dwordx4 v[152:155], v146, s[36:37] offset:512
	global_load_dwordx4 v[156:159], v146, s[36:37] offset:576
	s_waitcnt vmcnt(12)
	v_pk_fma_f32 v[168:169], v[124:125], v[112:113], v[168:169]
	v_pk_fma_f32 v[170:171], v[126:127], v[114:115], v[170:171]
	v_pk_fma_f32 v[172:173], v[120:121], v[116:117], v[172:173]
	v_pk_fma_f32 v[174:175], v[122:123], v[118:119], v[174:175]
	global_store_dwordx4 v146, v[168:171], s[36:37]
	global_store_dwordx4 v146, v[172:175], s[36:37] offset:64
	global_load_dwordx4 v[160:163], v147, s[36:37] offset:512
	global_load_dwordx4 v[164:167], v147, s[36:37] offset:576
	s_waitcnt vmcnt(14)
	v_pk_fma_f32 v[176:177], v[68:69], v[112:113], v[176:177]
	v_pk_fma_f32 v[178:179], v[70:71], v[114:115], v[178:179]
	v_pk_fma_f32 v[180:181], v[64:65], v[116:117], v[180:181]
	v_pk_fma_f32 v[182:183], v[66:67], v[118:119], v[182:183]
	global_store_dwordx4 v147, v[176:179], s[36:37]
	global_store_dwordx4 v147, v[180:183], s[36:37] offset:64
	global_load_dwordx4 v[168:171], v144, s[38:39]
	global_load_dwordx4 v[172:175], v144, s[38:39] offset:64
	s_waitcnt vmcnt(16)
	v_pk_fma_f32 v[184:185], v[108:109], v[200:201], v[184:185]
	v_pk_fma_f32 v[186:187], v[110:111], v[202:203], v[186:187]
	v_pk_fma_f32 v[188:189], v[104:105], v[204:205], v[188:189]
	v_pk_fma_f32 v[190:191], v[106:107], v[206:207], v[190:191]
	global_store_dwordx4 v144, v[184:187], s[36:37] offset:512
	global_store_dwordx4 v144, v[188:191], s[36:37] offset:576
	global_load_dwordx4 v[176:179], v145, s[38:39]
	global_load_dwordx4 v[180:183], v145, s[38:39] offset:64
	s_waitcnt vmcnt(16)
	v_pk_fma_f32 v[192:193], v[100:101], v[200:201], v[192:193]
	v_pk_fma_f32 v[194:195], v[102:103], v[202:203], v[194:195]
	v_pk_fma_f32 v[196:197], v[96:97], v[204:205], v[196:197]
	v_pk_fma_f32 v[198:199], v[98:99], v[206:207], v[198:199]
	global_store_dwordx4 v145, v[192:195], s[36:37] offset:512
	global_store_dwordx4 v145, v[196:199], s[36:37] offset:576
	global_load_dwordx4 v[184:187], v146, s[38:39]
	global_load_dwordx4 v[188:191], v146, s[38:39] offset:64
	s_waitcnt vmcnt(16)
;   DEVI void operator()(int row, int colb, int fq, const f32x4& a0, const f32x4& a1, float& sqacc, const int slice, const Pre& q) const {
;     ...
;     const float* src = row < TL ? xin_lat + (size_t)row * D : xin_ctx + (size_t)(row - TL) * D;
;     const f32x4 xi0 = *(const f32x4*)(src + colb + 4 * fq), xi1 = *(const f32x4*)(src + colb + 16 + 4 * fq);
; #pragma unroll
;     for (int n = 0; n < 2; ++n) {
;       const int col = colb + n * 16 + 4 * fq;
;       const f32x4& a = n ? a1 : a0; const f32x4& xi = n ? xi1 : xi0;
;       f32x4 o;
; #pragma unroll
;       for (int j = 0; j < 4; ++j) o[j] = xi[j] + coef * q.gv[n][j] * a[j];
;       *(f32x4*)(xout + (size_t)row * D + col) = o;
	v_pk_fma_f32 v[152:153], v[92:93], v[200:201], v[152:153]
	v_pk_fma_f32 v[154:155], v[94:95], v[202:203], v[154:155]
	v_pk_fma_f32 v[156:157], v[88:89], v[204:205], v[156:157]
	v_pk_fma_f32 v[158:159], v[90:91], v[206:207], v[158:159]
	global_store_dwordx4 v146, v[152:155], s[36:37] offset:512
	global_store_dwordx4 v146, v[156:159], s[36:37] offset:576
	global_load_dwordx4 v[192:195], v147, s[38:39]
	global_load_dwordx4 v[196:199], v147, s[38:39] offset:64
	s_waitcnt vmcnt(16)
	v_pk_fma_f32 v[160:161], v[84:85], v[200:201], v[160:161]
	v_pk_fma_f32 v[162:163], v[86:87], v[202:203], v[162:163]
	v_pk_fma_f32 v[164:165], v[80:81], v[204:205], v[164:165]
	v_pk_fma_f32 v[166:167], v[82:83], v[206:207], v[166:167]
	global_store_dwordx4 v147, v[160:163], s[36:37] offset:512
	global_store_dwordx4 v147, v[164:167], s[36:37] offset:576
	global_load_dwordx4 v[152:155], v144, s[38:39] offset:512
	global_load_dwordx4 v[156:159], v144, s[38:39] offset:576
	s_waitcnt vmcnt(16)
	v_pk_fma_f32 v[168:169], v[76:77], v[112:113], v[168:169]
	v_pk_fma_f32 v[170:171], v[78:79], v[114:115], v[170:171]
	v_pk_fma_f32 v[172:173], v[72:73], v[116:117], v[172:173]
	v_pk_fma_f32 v[174:175], v[74:75], v[118:119], v[174:175]
	global_store_dwordx4 v144, v[168:171], s[38:39]
	global_store_dwordx4 v144, v[172:175], s[38:39] offset:64
	global_load_dwordx4 v[160:163], v145, s[38:39] offset:512
	global_load_dwordx4 v[164:167], v145, s[38:39] offset:576
	s_waitcnt vmcnt(16)
	v_pk_fma_f32 v[176:177], v[60:61], v[112:113], v[176:177]
	v_pk_fma_f32 v[178:179], v[62:63], v[114:115], v[178:179]
	v_pk_fma_f32 v[180:181], v[56:57], v[116:117], v[180:181]
	v_pk_fma_f32 v[182:183], v[58:59], v[118:119], v[182:183]
	global_store_dwordx4 v145, v[176:179], s[38:39]
	global_store_dwordx4 v145, v[180:183], s[38:39] offset:64
	global_load_dwordx4 v[168:171], v146, s[38:39] offset:512
	global_load_dwordx4 v[172:175], v146, s[38:39] offset:576
	s_waitcnt vmcnt(16)
	v_pk_fma_f32 v[184:185], v[52:53], v[112:113], v[184:185]
	v_pk_fma_f32 v[186:187], v[54:55], v[114:115], v[186:187]
	v_pk_fma_f32 v[188:189], v[48:49], v[116:117], v[188:189]
	v_pk_fma_f32 v[190:191], v[50:51], v[118:119], v[190:191]
	global_store_dwordx4 v146, v[184:187], s[38:39]
	global_store_dwordx4 v146, v[188:191], s[38:39] offset:64
	global_load_dwordx4 v[176:179], v147, s[38:39] offset:512
	global_load_dwordx4 v[180:183], v147, s[38:39] offset:576
	s_waitcnt vmcnt(16)
	v_pk_fma_f32 v[192:193], v[44:45], v[112:113], v[192:193]
	v_pk_fma_f32 v[194:195], v[46:47], v[114:115], v[194:195]
	v_pk_fma_f32 v[196:197], v[40:41], v[116:117], v[196:197]
	v_pk_fma_f32 v[198:199], v[42:43], v[118:119], v[198:199]
	global_store_dwordx4 v147, v[192:195], s[38:39]
	global_store_dwordx4 v147, v[196:199], s[38:39] offset:64
	s_waitcnt vmcnt(14)
	v_pk_fma_f32 v[152:153], v[36:37], v[200:201], v[152:153]
	v_pk_fma_f32 v[154:155], v[38:39], v[202:203], v[154:155]
	v_pk_fma_f32 v[156:157], v[32:33], v[204:205], v[156:157]
	v_pk_fma_f32 v[158:159], v[34:35], v[206:207], v[158:159]
	global_store_dwordx4 v144, v[152:155], s[38:39] offset:512
	global_store_dwordx4 v144, v[156:159], s[38:39] offset:576
	s_waitcnt vmcnt(12)
	v_pk_fma_f32 v[160:161], v[28:29], v[200:201], v[160:161]
	v_pk_fma_f32 v[162:163], v[30:31], v[202:203], v[162:163]
	v_pk_fma_f32 v[164:165], v[24:25], v[204:205], v[164:165]
	v_pk_fma_f32 v[166:167], v[26:27], v[206:207], v[166:167]
	global_store_dwordx4 v145, v[160:163], s[38:39] offset:512
	global_store_dwordx4 v145, v[164:167], s[38:39] offset:576
	s_waitcnt vmcnt(10)
	v_pk_fma_f32 v[168:169], v[20:21], v[200:201], v[168:169]
	v_pk_fma_f32 v[170:171], v[22:23], v[202:203], v[170:171]
	v_pk_fma_f32 v[172:173], v[16:17], v[204:205], v[172:173]
	v_pk_fma_f32 v[174:175], v[18:19], v[206:207], v[174:175]
	global_store_dwordx4 v146, v[168:171], s[38:39] offset:512
	global_store_dwordx4 v146, v[172:175], s[38:39] offset:576
	s_waitcnt vmcnt(8)
	v_pk_fma_f32 v[176:177], v[12:13], v[200:201], v[176:177]
	v_pk_fma_f32 v[178:179], v[14:15], v[202:203], v[178:179]
	v_pk_fma_f32 v[180:181], v[8:9], v[204:205], v[180:181]
	v_pk_fma_f32 v[182:183], v[10:11], v[206:207], v[182:183]
	global_store_dwordx4 v147, v[176:179], s[38:39] offset:512
	global_store_dwordx4 v147, v[180:183], s[38:39] offset:576
	s_mov_b32 s90, -1
	s_branch .LBB0_1705
